# v8: as v6 but the original P8 epilogue restored (probe showed the hoisted-load P8 epilogue +11 us slower); P5 hoisted epilogue kept
# baseline (speedup 1.0000x reference)
; __device__ __forceinline__ unsigned pk2(float lo, float hi) { f32x2 v = {lo, hi}; bf16x2_t b = __builtin_convertvector(v, bf16x2_t); return __builtin_bit_cast(unsigned, b); }
; __device__ __forceinline__ float bf_lo(unsigned u) { return __uint_as_float(u << 16); }
; __device__ __forceinline__ float bf_hi(unsigned u) { return __uint_as_float(u & 0xffff0000u); }
;     __device__ __forceinline__ void operator()(const AccT& acc, const Unit& u, int wr, int wc, int fr, int fq) const {
;         const int row0 = u.pm * BM + wr * 64 + fr; const int col0 = u.pn * BM + wc * 32 + 8 * fq; const int b = row0 >> 12;
;         f32x4 gt[2][2];
; #pragma unroll
;         for (int bj = 0; bj < 2; ++bj)
; #pragma unroll
;             for (int n = 0; n < 2; ++n) gt[bj][n] = *(const f32x4*)(gate + (size_t)b * NMOD + col0 + bj * HALF + n * 4);
; #pragma unroll
;         for (int ai = 0; ai < 2; ++ai)
; #pragma unroll
;             for (int m = 0; m < 4; ++m) { const size_t off = (size_t)(row0 + ai * HALF + m * 16) * DM + col0;
; #pragma unroll
;                 for (int bj = 0; bj < 2; ++bj) { f32x4 b0, b1;
;                     if constexpr (BB) { const u32x4 w = *(const u32x4*)((const bf16_t*)base + off + bj * HALF);
;                         b0 = (f32x4){bf_lo(w.x), bf_hi(w.x), bf_lo(w.y), bf_hi(w.y)}; b1 = (f32x4){bf_lo(w.z), bf_hi(w.z), bf_lo(w.w), bf_hi(w.w)}; }
;                     else { b0 = __builtin_nontemporal_load((const f32x4*)((const float*)base + off + bj * HALF)); b1 = __builtin_nontemporal_load((const f32x4*)((const float*)base + off + bj * HALF + 4)); }
;                     const f32x4 o0 = b0 + gt[bj][0] * acc[ai][bj][m][0], o1 = b1 + gt[bj][1] * acc[ai][bj][m][1];
;                     if constexpr (OB) { u32x4 w; w.x = pk2(o0[0], o0[1]); w.y = pk2(o0[2], o0[3]); w.z = pk2(o1[0], o1[1]); w.w = pk2(o1[2], o1[3]);
;                         *(u32x4*)((bf16_t*)out + off + bj * HALF) = w; }
;                     else { __builtin_nontemporal_store(o0, (f32x4*)((float*)out + off + bj * HALF)); __builtin_nontemporal_store(o1, (f32x4*)((float*)out + off + bj * HALF + 4)); } } }
.LBB0_769:
	s_lshl_b32 s24, s52, 8
	s_add_i32 s24, s24, s44
	v_or_b32_e32 v164, s24, v166
	v_lshl_or_b32 v162, s53, 8, v168
	v_ashrrev_i32_e32 v165, 31, v164
	v_ashrrev_i32_e32 v163, 31, v162
	v_lshlrev_b64 v[120:121], 10, v[164:165]
	s_ashr_i32 s24, s24, 12
	v_lshl_add_u64 v[160:161], v[120:121], 0, v[162:163]
	s_mul_hi_i32 s25, s24, 0x6000
	s_mulk_i32 s24, 0x6000
	v_lshl_add_u64 v[176:177], v[160:161], 1, s[8:9]
	s_add_u32 s24, s42, s24
	global_load_dwordx4 v[172:175], v[176:177], off
	s_addc_u32 s25, s43, s25
	v_lshl_add_u64 v[124:125], v[162:163], 2, s[24:25]
	global_load_dwordx4 v[140:143], v[124:125], off
	global_load_dwordx4 v[136:139], v[124:125], off offset:16
	v_lshl_add_u64 v[178:179], v[160:161], 2, s[64:65]
	global_load_dwordx4 v[120:123], v[124:125], off offset:528
	s_nop 0
	global_load_dwordx4 v[124:127], v[124:125], off offset:512
	s_and_b64 vcc, exec, s[0:1]
	s_mov_b64 s[0:1], -1
	s_waitcnt vmcnt(0)
	v_lshlrev_b32_e32 v180, 16, v172
	v_and_b32_e32 v181, 0xffff0000, v172
	v_lshlrev_b32_e32 v172, 16, v173
	v_and_b32_e32 v173, 0xffff0000, v173
	v_lshlrev_b32_e32 v182, 16, v174
	v_and_b32_e32 v183, 0xffff0000, v174
	v_lshlrev_b32_e32 v174, 16, v175
	v_and_b32_e32 v175, 0xffff0000, v175
	v_pk_fma_f32 v[134:135], v[134:135], v[142:143], v[172:173]
	v_pk_fma_f32 v[132:133], v[132:133], v[140:141], v[180:181]
	v_pk_fma_f32 v[130:131], v[130:131], v[138:139], v[174:175]
	v_pk_fma_f32 v[128:129], v[128:129], v[136:137], v[182:183]
	global_store_dwordx4 v[178:179], v[132:135], off nt
	global_store_dwordx4 v[178:179], v[128:131], off offset:16 nt
	global_load_dwordx4 v[128:131], v[176:177], off offset:256
	v_or_b32_e32 v132, 16, v164
	v_ashrrev_i32_e32 v133, 31, v132
	v_lshlrev_b64 v[132:133], 10, v[132:133]
	v_lshl_add_u64 v[132:133], v[132:133], 0, v[162:163]
	v_lshl_add_u64 v[134:135], v[132:133], 1, s[8:9]
	s_waitcnt vmcnt(0)
	v_lshlrev_b32_e32 v172, 16, v128
	v_and_b32_e32 v173, 0xffff0000, v128
	v_lshlrev_b32_e32 v128, 16, v129
	v_and_b32_e32 v129, 0xffff0000, v129
	v_lshlrev_b32_e32 v174, 16, v130
	v_and_b32_e32 v175, 0xffff0000, v130
	v_lshlrev_b32_e32 v130, 16, v131
	v_and_b32_e32 v131, 0xffff0000, v131
	v_pk_fma_f32 v[118:119], v[118:119], v[126:127], v[128:129]
	v_pk_fma_f32 v[116:117], v[116:117], v[124:125], v[172:173]
	v_pk_fma_f32 v[114:115], v[114:115], v[122:123], v[130:131]
	v_pk_fma_f32 v[112:113], v[112:113], v[120:121], v[174:175]
	global_store_dwordx4 v[178:179], v[116:119], off offset:512 nt
	global_store_dwordx4 v[178:179], v[112:115], off offset:528 nt
	global_load_dwordx4 v[112:115], v[134:135], off
	v_lshl_add_u64 v[116:117], v[132:133], 2, s[64:65]
	s_waitcnt vmcnt(0)
	v_lshlrev_b32_e32 v118, 16, v112
	v_and_b32_e32 v119, 0xffff0000, v112
	v_lshlrev_b32_e32 v112, 16, v113
	v_and_b32_e32 v113, 0xffff0000, v113
	v_lshlrev_b32_e32 v128, 16, v114
	v_and_b32_e32 v129, 0xffff0000, v114
	v_lshlrev_b32_e32 v114, 16, v115
	v_and_b32_e32 v115, 0xffff0000, v115
	v_pk_fma_f32 v[110:111], v[110:111], v[142:143], v[112:113]
	v_pk_fma_f32 v[108:109], v[108:109], v[140:141], v[118:119]
	v_pk_fma_f32 v[106:107], v[106:107], v[138:139], v[114:115]
	v_pk_fma_f32 v[104:105], v[104:105], v[136:137], v[128:129]
	global_store_dwordx4 v[116:117], v[108:111], off nt
	global_store_dwordx4 v[116:117], v[104:107], off offset:16 nt
	global_load_dwordx4 v[104:107], v[134:135], off offset:256
	v_or_b32_e32 v108, 32, v164
	v_ashrrev_i32_e32 v109, 31, v108
	v_lshlrev_b64 v[108:109], 10, v[108:109]
	v_lshl_add_u64 v[108:109], v[108:109], 0, v[162:163]
	v_lshl_add_u64 v[110:111], v[108:109], 1, s[8:9]
	s_waitcnt vmcnt(0)
	v_lshlrev_b32_e32 v112, 16, v104
	v_and_b32_e32 v113, 0xffff0000, v104
	v_lshlrev_b32_e32 v104, 16, v105
	v_and_b32_e32 v105, 0xffff0000, v105
	v_lshlrev_b32_e32 v114, 16, v106
	v_and_b32_e32 v115, 0xffff0000, v106
	v_lshlrev_b32_e32 v106, 16, v107
	v_and_b32_e32 v107, 0xffff0000, v107
	v_pk_fma_f32 v[102:103], v[102:103], v[126:127], v[104:105]
	v_pk_fma_f32 v[100:101], v[100:101], v[124:125], v[112:113]
	v_pk_fma_f32 v[98:99], v[98:99], v[122:123], v[106:107]
	v_pk_fma_f32 v[96:97], v[96:97], v[120:121], v[114:115]
	global_store_dwordx4 v[116:117], v[100:103], off offset:512 nt
	global_store_dwordx4 v[116:117], v[96:99], off offset:528 nt
	global_load_dwordx4 v[96:99], v[110:111], off
	v_lshl_add_u64 v[100:101], v[108:109], 2, s[64:65]
	s_waitcnt vmcnt(0)
	v_lshlrev_b32_e32 v102, 16, v96
	v_and_b32_e32 v103, 0xffff0000, v96
	v_lshlrev_b32_e32 v96, 16, v97
	v_and_b32_e32 v97, 0xffff0000, v97
	v_lshlrev_b32_e32 v104, 16, v98
	v_and_b32_e32 v105, 0xffff0000, v98
	v_lshlrev_b32_e32 v98, 16, v99
	v_and_b32_e32 v99, 0xffff0000, v99
	v_pk_fma_f32 v[94:95], v[94:95], v[142:143], v[96:97]
	v_pk_fma_f32 v[92:93], v[92:93], v[140:141], v[102:103]
	v_pk_fma_f32 v[90:91], v[90:91], v[138:139], v[98:99]
	v_pk_fma_f32 v[88:89], v[88:89], v[136:137], v[104:105]
	global_store_dwordx4 v[100:101], v[92:95], off nt
	global_store_dwordx4 v[100:101], v[88:91], off offset:16 nt
	global_load_dwordx4 v[88:91], v[110:111], off offset:256
	v_or_b32_e32 v92, 48, v164
	v_ashrrev_i32_e32 v93, 31, v92
	v_lshlrev_b64 v[92:93], 10, v[92:93]
	v_lshl_add_u64 v[92:93], v[92:93], 0, v[162:163]
	v_lshl_add_u64 v[94:95], v[92:93], 1, s[8:9]
	s_waitcnt vmcnt(0)
	v_lshlrev_b32_e32 v96, 16, v88
	v_and_b32_e32 v97, 0xffff0000, v88
	v_lshlrev_b32_e32 v88, 16, v89
	v_and_b32_e32 v89, 0xffff0000, v89
	v_lshlrev_b32_e32 v98, 16, v90
	v_and_b32_e32 v99, 0xffff0000, v90
	v_lshlrev_b32_e32 v90, 16, v91
	v_and_b32_e32 v91, 0xffff0000, v91
	v_pk_fma_f32 v[86:87], v[86:87], v[126:127], v[88:89]
	v_pk_fma_f32 v[84:85], v[84:85], v[124:125], v[96:97]
	v_pk_fma_f32 v[82:83], v[82:83], v[122:123], v[90:91]
	v_pk_fma_f32 v[80:81], v[80:81], v[120:121], v[98:99]
	global_store_dwordx4 v[100:101], v[84:87], off offset:512 nt
	global_store_dwordx4 v[100:101], v[80:83], off offset:528 nt
	global_load_dwordx4 v[80:83], v[94:95], off
	v_lshl_add_u64 v[84:85], v[92:93], 2, s[64:65]
	s_waitcnt vmcnt(0)
; __device__ __forceinline__ unsigned pk2(float lo, float hi) { f32x2 v = {lo, hi}; bf16x2_t b = __builtin_convertvector(v, bf16x2_t); return __builtin_bit_cast(unsigned, b); }
; __device__ __forceinline__ float bf_lo(unsigned u) { return __uint_as_float(u << 16); }
; __device__ __forceinline__ float bf_hi(unsigned u) { return __uint_as_float(u & 0xffff0000u); }
;     __device__ __forceinline__ void operator()(const AccT& acc, const Unit& u, int wr, int wc, int fr, int fq) const {
;     ...
;         for (int ai = 0; ai < 2; ++ai)
; #pragma unroll
;             for (int m = 0; m < 4; ++m) { const size_t off = (size_t)(row0 + ai * HALF + m * 16) * DM + col0;
; #pragma unroll
;                 for (int bj = 0; bj < 2; ++bj) { f32x4 b0, b1;
;                     if constexpr (BB) { const u32x4 w = *(const u32x4*)((const bf16_t*)base + off + bj * HALF);
;                         b0 = (f32x4){bf_lo(w.x), bf_hi(w.x), bf_lo(w.y), bf_hi(w.y)}; b1 = (f32x4){bf_lo(w.z), bf_hi(w.z), bf_lo(w.w), bf_hi(w.w)}; }
;                     else { b0 = __builtin_nontemporal_load((const f32x4*)((const float*)base + off + bj * HALF)); b1 = __builtin_nontemporal_load((const f32x4*)((const float*)base + off + bj * HALF + 4)); }
;                     const f32x4 o0 = b0 + gt[bj][0] * acc[ai][bj][m][0], o1 = b1 + gt[bj][1] * acc[ai][bj][m][1];
;                     if constexpr (OB) { u32x4 w; w.x = pk2(o0[0], o0[1]); w.y = pk2(o0[2], o0[3]); w.z = pk2(o1[0], o1[1]); w.w = pk2(o1[2], o1[3]);
;                         *(u32x4*)((bf16_t*)out + off + bj * HALF) = w; }
;                     else { __builtin_nontemporal_store(o0, (f32x4*)((float*)out + off + bj * HALF)); __builtin_nontemporal_store(o1, (f32x4*)((float*)out + off + bj * HALF + 4)); } } }
	v_lshlrev_b32_e32 v86, 16, v80
	v_and_b32_e32 v87, 0xffff0000, v80
	v_lshlrev_b32_e32 v80, 16, v81
	v_and_b32_e32 v81, 0xffff0000, v81
	v_lshlrev_b32_e32 v88, 16, v82
	v_and_b32_e32 v89, 0xffff0000, v82
	v_lshlrev_b32_e32 v82, 16, v83
	v_and_b32_e32 v83, 0xffff0000, v83
	v_pk_fma_f32 v[78:79], v[78:79], v[142:143], v[80:81]
	v_pk_fma_f32 v[76:77], v[76:77], v[140:141], v[86:87]
	v_pk_fma_f32 v[74:75], v[74:75], v[138:139], v[82:83]
	v_pk_fma_f32 v[72:73], v[72:73], v[136:137], v[88:89]
	global_store_dwordx4 v[84:85], v[76:79], off nt
	global_store_dwordx4 v[84:85], v[72:75], off offset:16 nt
	global_load_dwordx4 v[72:75], v[94:95], off offset:256
	v_lshl_add_u64 v[76:77], v[160:161], 0, s[14:15]
	v_lshl_add_u64 v[78:79], v[76:77], 1, s[8:9]
	s_waitcnt vmcnt(0)
	v_lshlrev_b32_e32 v80, 16, v72
	v_and_b32_e32 v81, 0xffff0000, v72
	v_lshlrev_b32_e32 v72, 16, v73
	v_and_b32_e32 v73, 0xffff0000, v73
	v_lshlrev_b32_e32 v82, 16, v74
	v_and_b32_e32 v83, 0xffff0000, v74
	v_lshlrev_b32_e32 v74, 16, v75
	v_and_b32_e32 v75, 0xffff0000, v75
	v_pk_fma_f32 v[70:71], v[70:71], v[126:127], v[72:73]
	v_pk_fma_f32 v[68:69], v[68:69], v[124:125], v[80:81]
	v_pk_fma_f32 v[66:67], v[66:67], v[122:123], v[74:75]
	v_pk_fma_f32 v[64:65], v[64:65], v[120:121], v[82:83]
	global_store_dwordx4 v[84:85], v[68:71], off offset:512 nt
	global_store_dwordx4 v[84:85], v[64:67], off offset:528 nt
	global_load_dwordx4 v[64:67], v[78:79], off
	v_lshl_add_u64 v[68:69], v[76:77], 2, s[64:65]
	s_waitcnt vmcnt(0)
	v_lshlrev_b32_e32 v70, 16, v64
	v_and_b32_e32 v71, 0xffff0000, v64
	v_lshlrev_b32_e32 v64, 16, v65
	v_and_b32_e32 v65, 0xffff0000, v65
	v_lshlrev_b32_e32 v72, 16, v66
	v_and_b32_e32 v73, 0xffff0000, v66
	v_lshlrev_b32_e32 v66, 16, v67
	v_and_b32_e32 v67, 0xffff0000, v67
	v_pk_fma_f32 v[62:63], v[62:63], v[142:143], v[64:65]
	v_pk_fma_f32 v[60:61], v[60:61], v[140:141], v[70:71]
	v_pk_fma_f32 v[58:59], v[58:59], v[138:139], v[66:67]
	v_pk_fma_f32 v[56:57], v[56:57], v[136:137], v[72:73]
	global_store_dwordx4 v[68:69], v[60:63], off nt
	global_store_dwordx4 v[68:69], v[56:59], off offset:16 nt
	global_load_dwordx4 v[56:59], v[78:79], off offset:256
	v_lshl_add_u64 v[60:61], v[160:161], 0, s[16:17]
	v_lshl_add_u64 v[62:63], v[60:61], 1, s[8:9]
	s_waitcnt vmcnt(0)
	v_lshlrev_b32_e32 v64, 16, v56
	v_and_b32_e32 v65, 0xffff0000, v56
	v_lshlrev_b32_e32 v56, 16, v57
	v_and_b32_e32 v57, 0xffff0000, v57
	v_lshlrev_b32_e32 v66, 16, v58
	v_and_b32_e32 v67, 0xffff0000, v58
	v_lshlrev_b32_e32 v58, 16, v59
	v_and_b32_e32 v59, 0xffff0000, v59
	v_pk_fma_f32 v[54:55], v[54:55], v[126:127], v[56:57]
	v_pk_fma_f32 v[52:53], v[52:53], v[124:125], v[64:65]
	v_pk_fma_f32 v[50:51], v[50:51], v[122:123], v[58:59]
	v_pk_fma_f32 v[48:49], v[48:49], v[120:121], v[66:67]
	global_store_dwordx4 v[68:69], v[52:55], off offset:512 nt
	global_store_dwordx4 v[68:69], v[48:51], off offset:528 nt
	global_load_dwordx4 v[48:51], v[62:63], off
	v_lshl_add_u64 v[52:53], v[60:61], 2, s[64:65]
	s_waitcnt vmcnt(0)
	v_lshlrev_b32_e32 v54, 16, v48
	v_and_b32_e32 v55, 0xffff0000, v48
	v_lshlrev_b32_e32 v48, 16, v49
	v_and_b32_e32 v49, 0xffff0000, v49
	v_lshlrev_b32_e32 v56, 16, v50
	v_and_b32_e32 v57, 0xffff0000, v50
	v_lshlrev_b32_e32 v50, 16, v51
	v_and_b32_e32 v51, 0xffff0000, v51
	v_pk_fma_f32 v[46:47], v[46:47], v[142:143], v[48:49]
	v_pk_fma_f32 v[44:45], v[44:45], v[140:141], v[54:55]
	v_pk_fma_f32 v[42:43], v[42:43], v[138:139], v[50:51]
	v_pk_fma_f32 v[40:41], v[40:41], v[136:137], v[56:57]
	global_store_dwordx4 v[52:53], v[44:47], off nt
	global_store_dwordx4 v[52:53], v[40:43], off offset:16 nt
	global_load_dwordx4 v[40:43], v[62:63], off offset:256
	v_lshl_add_u64 v[44:45], v[160:161], 0, s[18:19]
	v_lshl_add_u64 v[46:47], v[44:45], 1, s[8:9]
	s_waitcnt vmcnt(0)
; __device__ __forceinline__ unsigned pk2(float lo, float hi) { f32x2 v = {lo, hi}; bf16x2_t b = __builtin_convertvector(v, bf16x2_t); return __builtin_bit_cast(unsigned, b); }
; __device__ __forceinline__ float bf_lo(unsigned u) { return __uint_as_float(u << 16); }
; __device__ __forceinline__ float bf_hi(unsigned u) { return __uint_as_float(u & 0xffff0000u); }
;     __device__ __forceinline__ void operator()(const AccT& acc, const Unit& u, int wr, int wc, int fr, int fq) const {
;     ...
;         for (int ai = 0; ai < 2; ++ai)
; #pragma unroll
;             for (int m = 0; m < 4; ++m) { const size_t off = (size_t)(row0 + ai * HALF + m * 16) * DM + col0;
; #pragma unroll
;                 for (int bj = 0; bj < 2; ++bj) { f32x4 b0, b1;
;                     if constexpr (BB) { const u32x4 w = *(const u32x4*)((const bf16_t*)base + off + bj * HALF);
;                         b0 = (f32x4){bf_lo(w.x), bf_hi(w.x), bf_lo(w.y), bf_hi(w.y)}; b1 = (f32x4){bf_lo(w.z), bf_hi(w.z), bf_lo(w.w), bf_hi(w.w)}; }
;                     else { b0 = __builtin_nontemporal_load((const f32x4*)((const float*)base + off + bj * HALF)); b1 = __builtin_nontemporal_load((const f32x4*)((const float*)base + off + bj * HALF + 4)); }
;                     const f32x4 o0 = b0 + gt[bj][0] * acc[ai][bj][m][0], o1 = b1 + gt[bj][1] * acc[ai][bj][m][1];
;                     if constexpr (OB) { u32x4 w; w.x = pk2(o0[0], o0[1]); w.y = pk2(o0[2], o0[3]); w.z = pk2(o1[0], o1[1]); w.w = pk2(o1[2], o1[3]);
;                         *(u32x4*)((bf16_t*)out + off + bj * HALF) = w; }
;                     else { __builtin_nontemporal_store(o0, (f32x4*)((float*)out + off + bj * HALF)); __builtin_nontemporal_store(o1, (f32x4*)((float*)out + off + bj * HALF + 4)); } } }
	v_lshlrev_b32_e32 v48, 16, v40
	v_and_b32_e32 v49, 0xffff0000, v40
	v_lshlrev_b32_e32 v40, 16, v41
	v_and_b32_e32 v41, 0xffff0000, v41
	v_lshlrev_b32_e32 v50, 16, v42
	v_and_b32_e32 v51, 0xffff0000, v42
	v_lshlrev_b32_e32 v42, 16, v43
	v_and_b32_e32 v43, 0xffff0000, v43
	v_pk_fma_f32 v[38:39], v[38:39], v[126:127], v[40:41]
	v_pk_fma_f32 v[36:37], v[36:37], v[124:125], v[48:49]
	v_pk_fma_f32 v[34:35], v[34:35], v[122:123], v[42:43]
	v_pk_fma_f32 v[32:33], v[32:33], v[120:121], v[50:51]
	global_store_dwordx4 v[52:53], v[36:39], off offset:512 nt
	global_store_dwordx4 v[52:53], v[32:35], off offset:528 nt
	global_load_dwordx4 v[32:35], v[46:47], off
	v_lshl_add_u64 v[36:37], v[44:45], 2, s[64:65]
	s_waitcnt vmcnt(0)
	v_lshlrev_b32_e32 v38, 16, v32
	v_and_b32_e32 v39, 0xffff0000, v32
	v_lshlrev_b32_e32 v32, 16, v33
	v_and_b32_e32 v33, 0xffff0000, v33
	v_lshlrev_b32_e32 v40, 16, v34
	v_and_b32_e32 v41, 0xffff0000, v34
	v_lshlrev_b32_e32 v34, 16, v35
	v_and_b32_e32 v35, 0xffff0000, v35
	v_pk_fma_f32 v[30:31], v[30:31], v[142:143], v[32:33]
	v_pk_fma_f32 v[28:29], v[28:29], v[140:141], v[38:39]
	v_pk_fma_f32 v[26:27], v[26:27], v[138:139], v[34:35]
	v_pk_fma_f32 v[24:25], v[24:25], v[136:137], v[40:41]
	global_store_dwordx4 v[36:37], v[28:31], off nt
	global_store_dwordx4 v[36:37], v[24:27], off offset:16 nt
	global_load_dwordx4 v[24:27], v[46:47], off offset:256
	v_lshl_add_u64 v[28:29], v[160:161], 0, s[20:21]
	v_lshl_add_u64 v[30:31], v[28:29], 1, s[8:9]
	s_waitcnt vmcnt(0)
	v_lshlrev_b32_e32 v32, 16, v24
	v_and_b32_e32 v33, 0xffff0000, v24
	v_lshlrev_b32_e32 v24, 16, v25
	v_and_b32_e32 v25, 0xffff0000, v25
	v_lshlrev_b32_e32 v34, 16, v26
	v_and_b32_e32 v35, 0xffff0000, v26
	v_lshlrev_b32_e32 v26, 16, v27
	v_and_b32_e32 v27, 0xffff0000, v27
	v_pk_fma_f32 v[22:23], v[22:23], v[126:127], v[24:25]
	v_pk_fma_f32 v[20:21], v[20:21], v[124:125], v[32:33]
	v_pk_fma_f32 v[18:19], v[18:19], v[122:123], v[26:27]
	v_pk_fma_f32 v[16:17], v[16:17], v[120:121], v[34:35]
	global_store_dwordx4 v[36:37], v[20:23], off offset:512 nt
	global_store_dwordx4 v[36:37], v[16:19], off offset:528 nt
	global_load_dwordx4 v[16:19], v[30:31], off
	v_lshl_add_u64 v[20:21], v[28:29], 2, s[64:65]
	s_waitcnt vmcnt(0)
	v_lshlrev_b32_e32 v22, 16, v16
	v_and_b32_e32 v23, 0xffff0000, v16
	v_lshlrev_b32_e32 v16, 16, v17
	v_and_b32_e32 v17, 0xffff0000, v17
	v_lshlrev_b32_e32 v24, 16, v18
	v_and_b32_e32 v25, 0xffff0000, v18
	v_lshlrev_b32_e32 v18, 16, v19
	v_and_b32_e32 v19, 0xffff0000, v19
	v_pk_fma_f32 v[14:15], v[14:15], v[142:143], v[16:17]
	v_pk_fma_f32 v[12:13], v[12:13], v[140:141], v[22:23]
	v_pk_fma_f32 v[10:11], v[10:11], v[138:139], v[18:19]
	v_pk_fma_f32 v[8:9], v[8:9], v[136:137], v[24:25]
	global_store_dwordx4 v[20:21], v[12:15], off nt
	global_store_dwordx4 v[20:21], v[8:11], off offset:16 nt
	global_load_dwordx4 v[8:11], v[30:31], off offset:256
	s_waitcnt vmcnt(0)
	v_lshlrev_b32_e32 v12, 16, v8
	v_and_b32_e32 v13, 0xffff0000, v8
	v_lshlrev_b32_e32 v8, 16, v9
	v_and_b32_e32 v9, 0xffff0000, v9
	v_lshlrev_b32_e32 v14, 16, v10
	v_and_b32_e32 v15, 0xffff0000, v10
	v_lshlrev_b32_e32 v10, 16, v11
	v_and_b32_e32 v11, 0xffff0000, v11
	v_pk_fma_f32 v[6:7], v[6:7], v[126:127], v[8:9]
	v_pk_fma_f32 v[4:5], v[4:5], v[124:125], v[12:13]
	v_pk_fma_f32 v[2:3], v[2:3], v[122:123], v[10:11]
	v_pk_fma_f32 v[0:1], v[0:1], v[120:121], v[14:15]
	global_store_dwordx4 v[20:21], v[4:7], off offset:512 nt
	global_store_dwordx4 v[20:21], v[0:3], off offset:528 nt
	s_cbranch_vccnz .LBB0_754
	s_andn2_b64 vcc, exec, s[6:7]
	s_cbranch_vccnz .LBB0_753
	s_barrier
	s_branch .LBB0_753
